# residual GEMM epilogue with 5 x-load groups in flight instead of 7
# speedup vs baseline: 1.0021x; 1.0017x over previous
.LBB0_149:
	s_or_b64 exec, exec, s[4:5]
	v_mov_b32_e32 v72, v154
	s_lshr_b32 s5, s12, 3
	v_and_b32_e32 v136, 15, v72
	v_lshrrev_b32_e32 v73, 1, v72
	v_ashrrev_i32_e32 v72, 2, v72
	s_lshl_b32 s4, s14, 8
	s_mul_i32 s5, s5, 0x9000
	v_and_b32_e32 v152, 0xffffffc0, v72
	s_add_u32 s12, s9, s5
	v_ashrrev_i32_e32 v153, 31, v152
	s_mov_b32 s5, s52
	v_and_b32_e32 v73, 0x78, v73
	v_lshl_add_u64 v[140:141], v[152:153], 0, s[4:5]
	v_lshl_or_b32 v146, s13, 8, v73
	v_or_b32_e32 v140, v140, v136
	v_ashrrev_i32_e32 v147, 31, v146
	v_lshlrev_b64 v[144:145], 10, v[140:141]
	s_addc_u32 s13, s10, 0
	v_lshl_add_u64 v[140:141], v[144:145], 0, v[146:147]
	v_lshl_add_u64 v[148:149], v[146:147], 2, s[12:13]
	v_lshlrev_b64 v[140:141], 2, v[140:141]
	s_nop 1
	v_readfirstlane_b32 s38, v140
	v_readfirstlane_b32 s39, v141
	s_nop 1
	v_subrev_u32_e32 v139, s38, v140
	s_add_u32 s40, s0, s38
	s_addc_u32 s41, s1, s39
	s_add_u32 s42, s70, s38
	s_addc_u32 s43, s71, s39
	s_mov_b64 s[44:45], s[40:41]
	s_mov_b64 s[46:47], s[42:43]
	global_load_dwordx4 v[234:237], v[148:149], off
	global_load_dwordx4 v[238:241], v[148:149], off offset:16
	global_load_dwordx4 v[242:245], v[148:149], off offset:512
	global_load_dwordx4 v[246:249], v[148:149], off offset:528
	global_load_dwordx4 v[178:181], v139, s[40:41]
	global_load_dwordx4 v[182:185], v139, s[40:41] offset:16
	s_add_u32 s40, s40, 0x10000
	s_addc_u32 s41, s41, 0
	global_load_dwordx4 v[186:189], v139, s[40:41]
	global_load_dwordx4 v[190:193], v139, s[40:41] offset:16
	s_add_u32 s40, s40, 0x10000
	s_addc_u32 s41, s41, 0
	global_load_dwordx4 v[194:197], v139, s[40:41]
	global_load_dwordx4 v[198:201], v139, s[40:41] offset:16
	s_add_u32 s40, s40, 0x10000
	s_addc_u32 s41, s41, 0
	global_load_dwordx4 v[202:205], v139, s[40:41]
	global_load_dwordx4 v[206:209], v139, s[40:41] offset:16
	s_add_u32 s40, s40, 0x50000
	s_addc_u32 s41, s41, 0
	global_load_dwordx4 v[210:213], v139, s[40:41]
	global_load_dwordx4 v[214:217], v139, s[40:41] offset:16
	s_add_u32 s40, s40, 0x10000
	s_addc_u32 s41, s41, 0
	s_waitcnt vmcnt(8)
	v_pk_mul_f32 v[132:133], v[132:133], v[234:235]
	v_pk_mul_f32 v[134:135], v[134:135], v[236:237]
	v_pk_mul_f32 v[128:129], v[128:129], v[238:239]
	v_pk_mul_f32 v[130:131], v[130:131], v[240:241]
	v_pk_fma_f32 v[132:133], v[132:133], 0.5, v[178:179] op_sel_hi:[1,0,1]
	v_pk_fma_f32 v[134:135], v[134:135], 0.5, v[180:181] op_sel_hi:[1,0,1]
	v_pk_fma_f32 v[128:129], v[128:129], 0.5, v[182:183] op_sel_hi:[1,0,1]
	v_pk_fma_f32 v[130:131], v[130:131], 0.5, v[184:185] op_sel_hi:[1,0,1]
	global_store_dwordx4 v139, v[132:135], s[42:43]
	global_store_dwordx4 v139, v[128:131], s[42:43] offset:16
	s_add_u32 s42, s42, 0x10000
	s_addc_u32 s43, s43, 0
	global_load_dwordx4 v[178:181], v139, s[40:41]
	global_load_dwordx4 v[182:185], v139, s[40:41] offset:16
	s_add_u32 s40, s40, 0x10000
	s_addc_u32 s41, s41, 0
	s_waitcnt vmcnt(10)
	v_pk_mul_f32 v[124:125], v[124:125], v[234:235]
	v_pk_mul_f32 v[126:127], v[126:127], v[236:237]
	v_pk_mul_f32 v[120:121], v[120:121], v[238:239]
	v_pk_mul_f32 v[122:123], v[122:123], v[240:241]
	v_pk_fma_f32 v[124:125], v[124:125], 0.5, v[186:187] op_sel_hi:[1,0,1]
	v_pk_fma_f32 v[126:127], v[126:127], 0.5, v[188:189] op_sel_hi:[1,0,1]
	v_pk_fma_f32 v[120:121], v[120:121], 0.5, v[190:191] op_sel_hi:[1,0,1]
	v_pk_fma_f32 v[122:123], v[122:123], 0.5, v[192:193] op_sel_hi:[1,0,1]
	global_store_dwordx4 v139, v[124:127], s[42:43]
	global_store_dwordx4 v139, v[120:123], s[42:43] offset:16
	s_add_u32 s42, s42, 0x10000
	s_addc_u32 s43, s43, 0
	global_load_dwordx4 v[186:189], v139, s[40:41]
	global_load_dwordx4 v[190:193], v139, s[40:41] offset:16
	s_add_u32 s40, s40, 0x10000
	s_addc_u32 s41, s41, 0
	s_waitcnt vmcnt(12)
	v_pk_mul_f32 v[116:117], v[116:117], v[234:235]
	v_pk_mul_f32 v[118:119], v[118:119], v[236:237]
	v_pk_mul_f32 v[112:113], v[112:113], v[238:239]
	v_pk_mul_f32 v[114:115], v[114:115], v[240:241]
	v_pk_fma_f32 v[116:117], v[116:117], 0.5, v[194:195] op_sel_hi:[1,0,1]
	v_pk_fma_f32 v[118:119], v[118:119], 0.5, v[196:197] op_sel_hi:[1,0,1]
	v_pk_fma_f32 v[112:113], v[112:113], 0.5, v[198:199] op_sel_hi:[1,0,1]
	v_pk_fma_f32 v[114:115], v[114:115], 0.5, v[200:201] op_sel_hi:[1,0,1]
	global_store_dwordx4 v139, v[116:119], s[42:43]
	global_store_dwordx4 v139, v[112:115], s[42:43] offset:16
	s_add_u32 s42, s42, 0x10000
	s_addc_u32 s43, s43, 0
	global_load_dwordx4 v[194:197], v139, s[40:41]
	global_load_dwordx4 v[198:201], v139, s[40:41] offset:16
	s_mov_b64 s[40:41], s[44:45]
	s_waitcnt vmcnt(14)
	v_pk_mul_f32 v[108:109], v[108:109], v[234:235]
	v_pk_mul_f32 v[110:111], v[110:111], v[236:237]
	v_pk_mul_f32 v[104:105], v[104:105], v[238:239]
	v_pk_mul_f32 v[106:107], v[106:107], v[240:241]
	v_pk_fma_f32 v[108:109], v[108:109], 0.5, v[202:203] op_sel_hi:[1,0,1]
	v_pk_fma_f32 v[110:111], v[110:111], 0.5, v[204:205] op_sel_hi:[1,0,1]
	v_pk_fma_f32 v[104:105], v[104:105], 0.5, v[206:207] op_sel_hi:[1,0,1]
	v_pk_fma_f32 v[106:107], v[106:107], 0.5, v[208:209] op_sel_hi:[1,0,1]
	global_store_dwordx4 v139, v[108:111], s[42:43]
	global_store_dwordx4 v139, v[104:107], s[42:43] offset:16
	s_add_u32 s42, s42, 0x50000
	s_addc_u32 s43, s43, 0
	global_load_dwordx4 v[202:205], v139, s[40:41] offset:512
	global_load_dwordx4 v[206:209], v139, s[40:41] offset:528
	s_add_u32 s40, s40, 0x10000
	s_addc_u32 s41, s41, 0
	s_waitcnt vmcnt(16)
	v_pk_mul_f32 v[100:101], v[100:101], v[234:235]
	v_pk_mul_f32 v[102:103], v[102:103], v[236:237]
	v_pk_mul_f32 v[96:97], v[96:97], v[238:239]
	v_pk_mul_f32 v[98:99], v[98:99], v[240:241]
	v_pk_fma_f32 v[100:101], v[100:101], 0.5, v[210:211] op_sel_hi:[1,0,1]
	v_pk_fma_f32 v[102:103], v[102:103], 0.5, v[212:213] op_sel_hi:[1,0,1]
	v_pk_fma_f32 v[96:97], v[96:97], 0.5, v[214:215] op_sel_hi:[1,0,1]
	v_pk_fma_f32 v[98:99], v[98:99], 0.5, v[216:217] op_sel_hi:[1,0,1]
	global_store_dwordx4 v139, v[100:103], s[42:43]
	global_store_dwordx4 v139, v[96:99], s[42:43] offset:16
	s_add_u32 s42, s42, 0x10000
	s_addc_u32 s43, s43, 0
	global_load_dwordx4 v[210:213], v139, s[40:41] offset:512
	global_load_dwordx4 v[214:217], v139, s[40:41] offset:528
	s_add_u32 s40, s40, 0x10000
	s_addc_u32 s41, s41, 0
	s_waitcnt vmcnt(16)
	v_pk_mul_f32 v[92:93], v[92:93], v[234:235]
	v_pk_mul_f32 v[94:95], v[94:95], v[236:237]
	v_pk_mul_f32 v[88:89], v[88:89], v[238:239]
	v_pk_mul_f32 v[90:91], v[90:91], v[240:241]
	v_pk_fma_f32 v[92:93], v[92:93], 0.5, v[178:179] op_sel_hi:[1,0,1]
	v_pk_fma_f32 v[94:95], v[94:95], 0.5, v[180:181] op_sel_hi:[1,0,1]
	v_pk_fma_f32 v[88:89], v[88:89], 0.5, v[182:183] op_sel_hi:[1,0,1]
	v_pk_fma_f32 v[90:91], v[90:91], 0.5, v[184:185] op_sel_hi:[1,0,1]
	global_store_dwordx4 v139, v[92:95], s[42:43]
	global_store_dwordx4 v139, v[88:91], s[42:43] offset:16
	s_add_u32 s42, s42, 0x10000
	s_addc_u32 s43, s43, 0
	global_load_dwordx4 v[178:181], v139, s[40:41] offset:512
	global_load_dwordx4 v[182:185], v139, s[40:41] offset:528
	s_add_u32 s40, s40, 0x10000
	s_addc_u32 s41, s41, 0
	s_waitcnt vmcnt(16)
	v_pk_mul_f32 v[84:85], v[84:85], v[234:235]
	v_pk_mul_f32 v[86:87], v[86:87], v[236:237]
	v_pk_mul_f32 v[80:81], v[80:81], v[238:239]
	v_pk_mul_f32 v[82:83], v[82:83], v[240:241]
	v_pk_fma_f32 v[84:85], v[84:85], 0.5, v[186:187] op_sel_hi:[1,0,1]
	v_pk_fma_f32 v[86:87], v[86:87], 0.5, v[188:189] op_sel_hi:[1,0,1]
	v_pk_fma_f32 v[80:81], v[80:81], 0.5, v[190:191] op_sel_hi:[1,0,1]
	v_pk_fma_f32 v[82:83], v[82:83], 0.5, v[192:193] op_sel_hi:[1,0,1]
	global_store_dwordx4 v139, v[84:87], s[42:43]
	global_store_dwordx4 v139, v[80:83], s[42:43] offset:16
	s_add_u32 s42, s42, 0x10000
	s_addc_u32 s43, s43, 0
	global_load_dwordx4 v[186:189], v139, s[40:41] offset:512
	global_load_dwordx4 v[190:193], v139, s[40:41] offset:528
	s_add_u32 s40, s40, 0x50000
	s_addc_u32 s41, s41, 0
	s_waitcnt vmcnt(16)
	v_pk_mul_f32 v[68:69], v[68:69], v[234:235]
	v_pk_mul_f32 v[70:71], v[70:71], v[236:237]
	v_pk_mul_f32 v[64:65], v[64:65], v[238:239]
	v_pk_mul_f32 v[66:67], v[66:67], v[240:241]
	v_pk_fma_f32 v[68:69], v[68:69], 0.5, v[194:195] op_sel_hi:[1,0,1]
	v_pk_fma_f32 v[70:71], v[70:71], 0.5, v[196:197] op_sel_hi:[1,0,1]
	v_pk_fma_f32 v[64:65], v[64:65], 0.5, v[198:199] op_sel_hi:[1,0,1]
	v_pk_fma_f32 v[66:67], v[66:67], 0.5, v[200:201] op_sel_hi:[1,0,1]
	global_store_dwordx4 v139, v[68:71], s[42:43]
	global_store_dwordx4 v139, v[64:67], s[42:43] offset:16
	s_mov_b64 s[42:43], s[46:47]
	global_load_dwordx4 v[194:197], v139, s[40:41] offset:512
	global_load_dwordx4 v[198:201], v139, s[40:41] offset:528
	s_add_u32 s40, s40, 0x10000
	s_addc_u32 s41, s41, 0
	s_waitcnt vmcnt(16)
	v_pk_mul_f32 v[60:61], v[60:61], v[242:243]
	v_pk_mul_f32 v[62:63], v[62:63], v[244:245]
	v_pk_mul_f32 v[56:57], v[56:57], v[246:247]
	v_pk_mul_f32 v[58:59], v[58:59], v[248:249]
	v_pk_fma_f32 v[60:61], v[60:61], 0.5, v[202:203] op_sel_hi:[1,0,1]
	v_pk_fma_f32 v[62:63], v[62:63], 0.5, v[204:205] op_sel_hi:[1,0,1]
	v_pk_fma_f32 v[56:57], v[56:57], 0.5, v[206:207] op_sel_hi:[1,0,1]
	v_pk_fma_f32 v[58:59], v[58:59], 0.5, v[208:209] op_sel_hi:[1,0,1]
	global_store_dwordx4 v139, v[60:63], s[42:43] offset:512
	global_store_dwordx4 v139, v[56:59], s[42:43] offset:528
	s_add_u32 s42, s42, 0x10000
	s_addc_u32 s43, s43, 0
	global_load_dwordx4 v[202:205], v139, s[40:41] offset:512
	global_load_dwordx4 v[206:209], v139, s[40:41] offset:528
	s_add_u32 s40, s40, 0x10000
	s_addc_u32 s41, s41, 0
	s_waitcnt vmcnt(16)
	v_pk_mul_f32 v[52:53], v[52:53], v[242:243]
	v_pk_mul_f32 v[54:55], v[54:55], v[244:245]
	v_pk_mul_f32 v[48:49], v[48:49], v[246:247]
	v_pk_mul_f32 v[50:51], v[50:51], v[248:249]
	v_pk_fma_f32 v[52:53], v[52:53], 0.5, v[210:211] op_sel_hi:[1,0,1]
	v_pk_fma_f32 v[54:55], v[54:55], 0.5, v[212:213] op_sel_hi:[1,0,1]
	v_pk_fma_f32 v[48:49], v[48:49], 0.5, v[214:215] op_sel_hi:[1,0,1]
	v_pk_fma_f32 v[50:51], v[50:51], 0.5, v[216:217] op_sel_hi:[1,0,1]
	global_store_dwordx4 v139, v[52:55], s[42:43] offset:512
	global_store_dwordx4 v139, v[48:51], s[42:43] offset:528
	s_add_u32 s42, s42, 0x10000
	s_addc_u32 s43, s43, 0
	global_load_dwordx4 v[210:213], v139, s[40:41] offset:512
	global_load_dwordx4 v[214:217], v139, s[40:41] offset:528
	s_add_u32 s40, s40, 0x10000
	s_addc_u32 s41, s41, 0
	s_waitcnt vmcnt(16)
	v_pk_mul_f32 v[44:45], v[44:45], v[242:243]
	v_pk_mul_f32 v[46:47], v[46:47], v[244:245]
	v_pk_mul_f32 v[40:41], v[40:41], v[246:247]
	v_pk_mul_f32 v[42:43], v[42:43], v[248:249]
	v_pk_fma_f32 v[44:45], v[44:45], 0.5, v[178:179] op_sel_hi:[1,0,1]
	v_pk_fma_f32 v[46:47], v[46:47], 0.5, v[180:181] op_sel_hi:[1,0,1]
	v_pk_fma_f32 v[40:41], v[40:41], 0.5, v[182:183] op_sel_hi:[1,0,1]
	v_pk_fma_f32 v[42:43], v[42:43], 0.5, v[184:185] op_sel_hi:[1,0,1]
	global_store_dwordx4 v139, v[44:47], s[42:43] offset:512
	global_store_dwordx4 v139, v[40:43], s[42:43] offset:528
	s_add_u32 s42, s42, 0x10000
	s_addc_u32 s43, s43, 0
	global_load_dwordx4 v[178:181], v139, s[40:41] offset:512
	global_load_dwordx4 v[182:185], v139, s[40:41] offset:528
	s_waitcnt vmcnt(16)
	v_pk_mul_f32 v[32:33], v[32:33], v[242:243]
	v_pk_mul_f32 v[34:35], v[34:35], v[244:245]
	v_pk_mul_f32 v[24:25], v[24:25], v[246:247]
	v_pk_mul_f32 v[26:27], v[26:27], v[248:249]
	v_pk_fma_f32 v[32:33], v[32:33], 0.5, v[186:187] op_sel_hi:[1,0,1]
	v_pk_fma_f32 v[34:35], v[34:35], 0.5, v[188:189] op_sel_hi:[1,0,1]
	v_pk_fma_f32 v[24:25], v[24:25], 0.5, v[190:191] op_sel_hi:[1,0,1]
	v_pk_fma_f32 v[26:27], v[26:27], 0.5, v[192:193] op_sel_hi:[1,0,1]
	global_store_dwordx4 v139, v[32:35], s[42:43] offset:512
	global_store_dwordx4 v139, v[24:27], s[42:43] offset:528
	s_add_u32 s42, s42, 0x50000
	s_addc_u32 s43, s43, 0
	s_waitcnt vmcnt(14)
	v_pk_mul_f32 v[36:37], v[36:37], v[242:243]
	v_pk_mul_f32 v[38:39], v[38:39], v[244:245]
	v_pk_mul_f32 v[28:29], v[28:29], v[246:247]
	v_pk_mul_f32 v[30:31], v[30:31], v[248:249]
	v_pk_fma_f32 v[36:37], v[36:37], 0.5, v[194:195] op_sel_hi:[1,0,1]
	v_pk_fma_f32 v[38:39], v[38:39], 0.5, v[196:197] op_sel_hi:[1,0,1]
	v_pk_fma_f32 v[28:29], v[28:29], 0.5, v[198:199] op_sel_hi:[1,0,1]
	v_pk_fma_f32 v[30:31], v[30:31], 0.5, v[200:201] op_sel_hi:[1,0,1]
	global_store_dwordx4 v139, v[36:39], s[42:43] offset:512
	global_store_dwordx4 v139, v[28:31], s[42:43] offset:528
	s_add_u32 s42, s42, 0x10000
	s_addc_u32 s43, s43, 0
	s_waitcnt vmcnt(12)
	v_pk_mul_f32 v[20:21], v[20:21], v[242:243]
	v_pk_mul_f32 v[22:23], v[22:23], v[244:245]
	v_pk_mul_f32 v[16:17], v[16:17], v[246:247]
	v_pk_mul_f32 v[18:19], v[18:19], v[248:249]
	v_pk_fma_f32 v[20:21], v[20:21], 0.5, v[202:203] op_sel_hi:[1,0,1]
	v_pk_fma_f32 v[22:23], v[22:23], 0.5, v[204:205] op_sel_hi:[1,0,1]
	v_pk_fma_f32 v[16:17], v[16:17], 0.5, v[206:207] op_sel_hi:[1,0,1]
	v_pk_fma_f32 v[18:19], v[18:19], 0.5, v[208:209] op_sel_hi:[1,0,1]
	global_store_dwordx4 v139, v[20:23], s[42:43] offset:512
	global_store_dwordx4 v139, v[16:19], s[42:43] offset:528
	s_add_u32 s42, s42, 0x10000
	s_addc_u32 s43, s43, 0
	s_waitcnt vmcnt(10)
	v_pk_mul_f32 v[12:13], v[12:13], v[242:243]
	v_pk_mul_f32 v[14:15], v[14:15], v[244:245]
	v_pk_mul_f32 v[8:9], v[8:9], v[246:247]
	v_pk_mul_f32 v[10:11], v[10:11], v[248:249]
	v_pk_fma_f32 v[12:13], v[12:13], 0.5, v[210:211] op_sel_hi:[1,0,1]
	v_pk_fma_f32 v[14:15], v[14:15], 0.5, v[212:213] op_sel_hi:[1,0,1]
	v_pk_fma_f32 v[8:9], v[8:9], 0.5, v[214:215] op_sel_hi:[1,0,1]
	v_pk_fma_f32 v[10:11], v[10:11], 0.5, v[216:217] op_sel_hi:[1,0,1]
	global_store_dwordx4 v139, v[12:15], s[42:43] offset:512
	global_store_dwordx4 v139, v[8:11], s[42:43] offset:528
	s_add_u32 s42, s42, 0x10000
	s_addc_u32 s43, s43, 0
	s_waitcnt vmcnt(8)
	v_pk_mul_f32 v[4:5], v[4:5], v[242:243]
	v_pk_mul_f32 v[6:7], v[6:7], v[244:245]
	v_pk_mul_f32 v[0:1], v[0:1], v[246:247]
	v_pk_mul_f32 v[2:3], v[2:3], v[248:249]
	v_pk_fma_f32 v[4:5], v[4:5], 0.5, v[178:179] op_sel_hi:[1,0,1]
	v_pk_fma_f32 v[6:7], v[6:7], 0.5, v[180:181] op_sel_hi:[1,0,1]
	v_pk_fma_f32 v[0:1], v[0:1], 0.5, v[182:183] op_sel_hi:[1,0,1]
	v_pk_fma_f32 v[2:3], v[2:3], 0.5, v[184:185] op_sel_hi:[1,0,1]
	global_store_dwordx4 v139, v[4:7], s[42:43] offset:512
	global_store_dwordx4 v139, v[0:3], s[42:43] offset:528
	v_pk_mul_f32 v[200:201], v[132:133], v[132:133]
	v_pk_mul_f32 v[202:203], v[124:125], v[124:125]
	v_pk_mul_f32 v[204:205], v[116:117], v[116:117]
	v_pk_mul_f32 v[206:207], v[108:109], v[108:109]
	v_pk_mul_f32 v[208:209], v[100:101], v[100:101]
	v_pk_mul_f32 v[210:211], v[92:93], v[92:93]
	v_pk_mul_f32 v[212:213], v[84:85], v[84:85]
	v_pk_mul_f32 v[214:215], v[68:69], v[68:69]
	v_pk_fma_f32 v[200:201], v[134:135], v[134:135], v[200:201]
	v_pk_fma_f32 v[202:203], v[126:127], v[126:127], v[202:203]
	v_pk_fma_f32 v[204:205], v[118:119], v[118:119], v[204:205]
	v_pk_fma_f32 v[206:207], v[110:111], v[110:111], v[206:207]
	v_pk_fma_f32 v[208:209], v[102:103], v[102:103], v[208:209]
	v_pk_fma_f32 v[210:211], v[94:95], v[94:95], v[210:211]
	v_pk_fma_f32 v[212:213], v[86:87], v[86:87], v[212:213]
	v_pk_fma_f32 v[214:215], v[70:71], v[70:71], v[214:215]
	v_pk_fma_f32 v[200:201], v[128:129], v[128:129], v[200:201]
	v_pk_fma_f32 v[202:203], v[120:121], v[120:121], v[202:203]
	v_pk_fma_f32 v[204:205], v[112:113], v[112:113], v[204:205]
	v_pk_fma_f32 v[206:207], v[104:105], v[104:105], v[206:207]
	v_pk_fma_f32 v[208:209], v[96:97], v[96:97], v[208:209]
	v_pk_fma_f32 v[210:211], v[88:89], v[88:89], v[210:211]
	v_pk_fma_f32 v[212:213], v[80:81], v[80:81], v[212:213]
	v_pk_fma_f32 v[214:215], v[64:65], v[64:65], v[214:215]
	v_pk_fma_f32 v[200:201], v[130:131], v[130:131], v[200:201]
	v_pk_fma_f32 v[202:203], v[122:123], v[122:123], v[202:203]
	v_pk_fma_f32 v[204:205], v[114:115], v[114:115], v[204:205]
	v_pk_fma_f32 v[206:207], v[106:107], v[106:107], v[206:207]
	v_pk_fma_f32 v[208:209], v[98:99], v[98:99], v[208:209]
	v_pk_fma_f32 v[210:211], v[90:91], v[90:91], v[210:211]
	v_pk_fma_f32 v[212:213], v[82:83], v[82:83], v[212:213]
	v_pk_fma_f32 v[214:215], v[66:67], v[66:67], v[214:215]
	v_pk_fma_f32 v[200:201], v[60:61], v[60:61], v[200:201]
	v_pk_fma_f32 v[202:203], v[52:53], v[52:53], v[202:203]
	v_pk_fma_f32 v[204:205], v[44:45], v[44:45], v[204:205]
	v_pk_fma_f32 v[206:207], v[32:33], v[32:33], v[206:207]
	v_pk_fma_f32 v[208:209], v[36:37], v[36:37], v[208:209]
	v_pk_fma_f32 v[210:211], v[20:21], v[20:21], v[210:211]
	v_pk_fma_f32 v[212:213], v[12:13], v[12:13], v[212:213]
	v_pk_fma_f32 v[214:215], v[4:5], v[4:5], v[214:215]
	v_pk_fma_f32 v[200:201], v[62:63], v[62:63], v[200:201]
	v_pk_fma_f32 v[202:203], v[54:55], v[54:55], v[202:203]
	v_pk_fma_f32 v[204:205], v[46:47], v[46:47], v[204:205]
	v_pk_fma_f32 v[206:207], v[34:35], v[34:35], v[206:207]
	v_pk_fma_f32 v[208:209], v[38:39], v[38:39], v[208:209]
	v_pk_fma_f32 v[210:211], v[22:23], v[22:23], v[210:211]
	v_pk_fma_f32 v[212:213], v[14:15], v[14:15], v[212:213]
	v_pk_fma_f32 v[214:215], v[6:7], v[6:7], v[214:215]
	v_pk_fma_f32 v[200:201], v[56:57], v[56:57], v[200:201]
	v_pk_fma_f32 v[202:203], v[48:49], v[48:49], v[202:203]
	v_pk_fma_f32 v[204:205], v[40:41], v[40:41], v[204:205]
	v_pk_fma_f32 v[206:207], v[24:25], v[24:25], v[206:207]
	v_pk_fma_f32 v[208:209], v[28:29], v[28:29], v[208:209]
	v_pk_fma_f32 v[210:211], v[16:17], v[16:17], v[210:211]
	v_pk_fma_f32 v[212:213], v[8:9], v[8:9], v[212:213]
	v_pk_fma_f32 v[214:215], v[0:1], v[0:1], v[214:215]
	v_pk_fma_f32 v[200:201], v[58:59], v[58:59], v[200:201]
	v_pk_fma_f32 v[202:203], v[50:51], v[50:51], v[202:203]
	v_pk_fma_f32 v[204:205], v[42:43], v[42:43], v[204:205]
	v_pk_fma_f32 v[206:207], v[26:27], v[26:27], v[206:207]
	v_pk_fma_f32 v[208:209], v[30:31], v[30:31], v[208:209]
	v_pk_fma_f32 v[210:211], v[18:19], v[18:19], v[210:211]
	v_pk_fma_f32 v[212:213], v[10:11], v[10:11], v[212:213]
	v_pk_fma_f32 v[214:215], v[2:3], v[2:3], v[214:215]
	v_add_f32_e32 v216, v200, v201
	v_add_f32_e32 v217, v202, v203
	v_add_f32_e32 v218, v204, v205
	v_add_f32_e32 v219, v206, v207
	v_add_f32_e32 v220, v208, v209
	v_add_f32_e32 v221, v210, v211
	v_add_f32_e32 v222, v212, v213
	v_add_f32_e32 v223, v214, v215
	v_and_b32_e32 v224, 63, v154
	v_xor_b32_e32 v225, 32, v224
	v_xor_b32_e32 v224, 16, v224
	v_lshlrev_b32_e32 v224, 2, v224
	v_lshlrev_b32_e32 v225, 2, v225
	ds_bpermute_b32 v226, v224, v216
	ds_bpermute_b32 v227, v224, v217
	ds_bpermute_b32 v228, v224, v218
	ds_bpermute_b32 v229, v224, v219
	ds_bpermute_b32 v230, v224, v220
	ds_bpermute_b32 v231, v224, v221
	ds_bpermute_b32 v232, v224, v222
	ds_bpermute_b32 v233, v224, v223
	s_waitcnt lgkmcnt(0)
	v_add_f32_e32 v216, v216, v226
	v_add_f32_e32 v217, v217, v227
	v_add_f32_e32 v218, v218, v228
	v_add_f32_e32 v219, v219, v229
	v_add_f32_e32 v220, v220, v230
	v_add_f32_e32 v221, v221, v231
	v_add_f32_e32 v222, v222, v232
	v_add_f32_e32 v223, v223, v233
	ds_bpermute_b32 v226, v225, v216
	ds_bpermute_b32 v227, v225, v217
	ds_bpermute_b32 v228, v225, v218
	ds_bpermute_b32 v229, v225, v219
	ds_bpermute_b32 v230, v225, v220
	ds_bpermute_b32 v231, v225, v221
	ds_bpermute_b32 v232, v225, v222
	ds_bpermute_b32 v233, v225, v223
	s_waitcnt lgkmcnt(0)
	v_add_f32_e32 v216, v216, v226
	v_add_f32_e32 v217, v217, v227
	v_add_f32_e32 v218, v218, v228
	v_add_f32_e32 v219, v219, v229
	v_add_f32_e32 v220, v220, v230
	v_add_f32_e32 v221, v221, v231
	v_add_f32_e32 v222, v222, v232
	v_add_f32_e32 v223, v223, v233
	v_bfe_u32 v234, v154, 6, 2
	v_lshlrev_b32_e32 v234, 8, v234
	v_lshrrev_b32_e32 v235, 8, v154
	v_lshl_add_u32 v234, v235, 6, v234
	v_and_b32_e32 v235, 15, v154
	v_add_u32_e32 v234, v234, v235
	v_lshlrev_b32_e32 v234, 2, v234
	ds_write_b32 v234, v216 offset:0
	ds_write_b32 v234, v217 offset:64
	ds_write_b32 v234, v218 offset:128
	ds_write_b32 v234, v219 offset:192
	ds_write_b32 v234, v220 offset:512
	ds_write_b32 v234, v221 offset:576
	ds_write_b32 v234, v222 offset:640
	ds_write_b32 v234, v223 offset:704
	s_waitcnt lgkmcnt(0)
	s_barrier
	v_cmp_gt_u32_e32 vcc, 0x100, v154
	s_and_saveexec_b64 s[48:49], vcc
	v_lshlrev_b32_e32 v235, 2, v154
	ds_read_b32 v236, v235
	ds_read_b32 v237, v235 offset:1024
	ds_read_b32 v238, v235 offset:2048
	ds_read_b32 v239, v235 offset:3072
	s_lshl_b32 s50, s6, 3
	s_and_b32 s50, s50, 56
	s_bfe_u32 s51, s6, 0x30003
	s_or_b32 s50, s50, s51
	s_lshl_b32 s50, s50, 2
	s_lshr_b32 s51, s6, 6
	s_or_b32 s50, s50, s51
	s_lshl_b32 s50, s50, 10
	s_add_u32 s50, s50, s72
	s_addc_u32 s51, s73, 0
	s_add_u32 s50, s50, 0x19500000
	s_addc_u32 s51, s51, 0
	s_waitcnt lgkmcnt(0)
	v_add_f32_e32 v236, v236, v237
	v_add_f32_e32 v238, v238, v239
	v_add_f32_e32 v236, v236, v238
	global_store_dword v235, v236, s[50:51]
	s_mov_b64 exec, s[48:49]
	s_mov_b32 s92, s6
	v_mov_b64_e32 v[242:243], v[0:1]
	v_mov_b64_e32 v[244:245], v[2:3]
	v_mov_b64_e32 v[246:247], v[4:5]
	v_mov_b64_e32 v[248:249], v[6:7]
	s_add_i32 s6, s6, s74
	s_add_i32 s11, s11, s20
	s_cmpk_lt_i32 s6, 0x100
	s_cbranch_scc0 .LBB0_156

.LBB0_587:
	s_or_b64 exec, exec, s[4:5]
	v_mov_b32_e32 v80, v154
	s_lshl_b32 s4, s15, 8
	v_and_b32_e32 v136, 15, v80
	v_lshrrev_b32_e32 v81, 1, v80
	v_ashrrev_i32_e32 v80, 2, v80
	v_and_b32_e32 v152, 0xffffffc0, v80
	v_ashrrev_i32_e32 v153, 31, v152
	s_mov_b32 s5, s52
	s_lshr_b32 s1, s14, 3
	v_and_b32_e32 v81, 0x78, v81
	v_lshl_add_u64 v[140:141], v[152:153], 0, s[4:5]
	v_lshl_or_b32 v144, s0, 8, v81
	s_mul_i32 s1, s1, 0x9000
	v_or_b32_e32 v140, v140, v136
	s_add_u32 s0, s11, s1
	v_ashrrev_i32_e32 v145, 31, v144
	v_lshlrev_b64 v[140:141], 12, v[140:141]
	s_addc_u32 s1, s12, 0
	v_lshlrev_b64 v[150:151], 2, v[144:145]
	v_lshl_add_u64 v[170:171], s[70:71], 0, v[140:141]
	v_lshl_add_u64 v[146:147], s[0:1], 0, v[150:151]
	v_lshl_add_u64 v[148:149], v[170:171], 0, v[150:151]
	s_nop 1
	v_readfirstlane_b32 s38, v148
	v_readfirstlane_b32 s39, v149
	s_nop 1
	v_subrev_u32_e32 v139, s38, v148
	s_mov_b64 s[40:41], s[38:39]
	s_mov_b64 s[42:43], s[38:39]
	s_mov_b64 s[44:45], s[40:41]
	s_mov_b64 s[46:47], s[42:43]
	s_mov_b64 s[36:37], 0x20000
	global_load_dwordx4 v[234:237], v[146:147], off
	global_load_dwordx4 v[238:241], v[146:147], off offset:16
	global_load_dwordx4 v[242:245], v[146:147], off offset:512
	global_load_dwordx4 v[246:249], v[146:147], off offset:528
	global_load_dwordx4 v[178:181], v139, s[40:41]
	global_load_dwordx4 v[182:185], v139, s[40:41] offset:16
	s_add_u32 s40, s40, 0x10000
	s_addc_u32 s41, s41, 0
	global_load_dwordx4 v[186:189], v139, s[40:41]
	global_load_dwordx4 v[190:193], v139, s[40:41] offset:16
	s_add_u32 s40, s40, 0x10000
	s_addc_u32 s41, s41, 0
	global_load_dwordx4 v[194:197], v139, s[40:41]
	global_load_dwordx4 v[198:201], v139, s[40:41] offset:16
	s_add_u32 s40, s40, 0x10000
	s_addc_u32 s41, s41, 0
	global_load_dwordx4 v[202:205], v139, s[40:41]
	global_load_dwordx4 v[206:209], v139, s[40:41] offset:16
	s_add_u32 s40, s40, 0x50000
	s_addc_u32 s41, s41, 0
	global_load_dwordx4 v[210:213], v139, s[40:41]
	global_load_dwordx4 v[214:217], v139, s[40:41] offset:16
	s_add_u32 s40, s40, 0x10000
	s_addc_u32 s41, s41, 0
	s_waitcnt vmcnt(8)
	v_pk_fma_f32 v[128:129], v[128:129], v[234:235], v[178:179]
	v_pk_fma_f32 v[130:131], v[130:131], v[236:237], v[180:181]
	v_pk_fma_f32 v[132:133], v[132:133], v[238:239], v[182:183]
	v_pk_fma_f32 v[134:135], v[134:135], v[240:241], v[184:185]
	global_store_dwordx4 v139, v[128:131], s[42:43]
	global_store_dwordx4 v139, v[132:135], s[42:43] offset:16
	s_add_u32 s42, s42, 0x10000
	s_addc_u32 s43, s43, 0
	global_load_dwordx4 v[178:181], v139, s[40:41]
	global_load_dwordx4 v[182:185], v139, s[40:41] offset:16
	s_add_u32 s40, s40, 0x10000
	s_addc_u32 s41, s41, 0
	s_waitcnt vmcnt(10)
	v_pk_fma_f32 v[124:125], v[124:125], v[234:235], v[186:187]
	v_pk_fma_f32 v[126:127], v[126:127], v[236:237], v[188:189]
	v_pk_fma_f32 v[120:121], v[120:121], v[238:239], v[190:191]
	v_pk_fma_f32 v[122:123], v[122:123], v[240:241], v[192:193]
	global_store_dwordx4 v139, v[124:127], s[42:43]
	global_store_dwordx4 v139, v[120:123], s[42:43] offset:16
	s_add_u32 s42, s42, 0x10000
	s_addc_u32 s43, s43, 0
	global_load_dwordx4 v[186:189], v139, s[40:41]
	global_load_dwordx4 v[190:193], v139, s[40:41] offset:16
	s_add_u32 s40, s40, 0x10000
	s_addc_u32 s41, s41, 0
	s_waitcnt vmcnt(12)
	v_pk_fma_f32 v[112:113], v[112:113], v[234:235], v[194:195]
	v_pk_fma_f32 v[114:115], v[114:115], v[236:237], v[196:197]
	v_pk_fma_f32 v[116:117], v[116:117], v[238:239], v[198:199]
	v_pk_fma_f32 v[118:119], v[118:119], v[240:241], v[200:201]
	global_store_dwordx4 v139, v[112:115], s[42:43]
	global_store_dwordx4 v139, v[116:119], s[42:43] offset:16
	s_add_u32 s42, s42, 0x10000
	s_addc_u32 s43, s43, 0
	global_load_dwordx4 v[194:197], v139, s[40:41]
	global_load_dwordx4 v[198:201], v139, s[40:41] offset:16
	s_mov_b64 s[40:41], s[44:45]
	s_waitcnt vmcnt(14)
	v_pk_fma_f32 v[100:101], v[100:101], v[234:235], v[202:203]
	v_pk_fma_f32 v[102:103], v[102:103], v[236:237], v[204:205]
	v_pk_fma_f32 v[96:97], v[96:97], v[238:239], v[206:207]
	v_pk_fma_f32 v[98:99], v[98:99], v[240:241], v[208:209]
	global_store_dwordx4 v139, v[100:103], s[42:43]
	global_store_dwordx4 v139, v[96:99], s[42:43] offset:16
	s_add_u32 s42, s42, 0x50000
	s_addc_u32 s43, s43, 0
	global_load_dwordx4 v[202:205], v139, s[40:41] offset:512
	global_load_dwordx4 v[206:209], v139, s[40:41] offset:528
	s_add_u32 s40, s40, 0x10000
	s_addc_u32 s41, s41, 0
	s_waitcnt vmcnt(16)
	v_pk_fma_f32 v[104:105], v[104:105], v[234:235], v[210:211]
	v_pk_fma_f32 v[106:107], v[106:107], v[236:237], v[212:213]
	v_pk_fma_f32 v[108:109], v[108:109], v[238:239], v[214:215]
	v_pk_fma_f32 v[110:111], v[110:111], v[240:241], v[216:217]
	global_store_dwordx4 v139, v[104:107], s[42:43]
	global_store_dwordx4 v139, v[108:111], s[42:43] offset:16
	s_add_u32 s42, s42, 0x10000
	s_addc_u32 s43, s43, 0
	global_load_dwordx4 v[210:213], v139, s[40:41] offset:512
	global_load_dwordx4 v[214:217], v139, s[40:41] offset:528
	s_add_u32 s40, s40, 0x10000
	s_addc_u32 s41, s41, 0
	s_waitcnt vmcnt(16)
	v_pk_fma_f32 v[92:93], v[92:93], v[234:235], v[178:179]
	v_pk_fma_f32 v[94:95], v[94:95], v[236:237], v[180:181]
	v_pk_fma_f32 v[84:85], v[84:85], v[238:239], v[182:183]
	v_pk_fma_f32 v[86:87], v[86:87], v[240:241], v[184:185]
	global_store_dwordx4 v139, v[92:95], s[42:43]
	global_store_dwordx4 v139, v[84:87], s[42:43] offset:16
	s_add_u32 s42, s42, 0x10000
	s_addc_u32 s43, s43, 0
	global_load_dwordx4 v[178:181], v139, s[40:41] offset:512
	global_load_dwordx4 v[182:185], v139, s[40:41] offset:528
	s_add_u32 s40, s40, 0x10000
	s_addc_u32 s41, s41, 0
	s_waitcnt vmcnt(16)
	v_pk_fma_f32 v[72:73], v[72:73], v[234:235], v[186:187]
	v_pk_fma_f32 v[74:75], v[74:75], v[236:237], v[188:189]
	v_pk_fma_f32 v[76:77], v[76:77], v[238:239], v[190:191]
	v_pk_fma_f32 v[78:79], v[78:79], v[240:241], v[192:193]
	global_store_dwordx4 v139, v[72:75], s[42:43]
	global_store_dwordx4 v139, v[76:79], s[42:43] offset:16
	s_add_u32 s42, s42, 0x10000
	s_addc_u32 s43, s43, 0
	global_load_dwordx4 v[186:189], v139, s[40:41] offset:512
	global_load_dwordx4 v[190:193], v139, s[40:41] offset:528
	s_add_u32 s40, s40, 0x50000
	s_addc_u32 s41, s41, 0
	s_waitcnt vmcnt(16)
	v_pk_fma_f32 v[68:69], v[68:69], v[234:235], v[194:195]
	v_pk_fma_f32 v[70:71], v[70:71], v[236:237], v[196:197]
	v_pk_fma_f32 v[64:65], v[64:65], v[238:239], v[198:199]
	v_pk_fma_f32 v[66:67], v[66:67], v[240:241], v[200:201]
	global_store_dwordx4 v139, v[68:71], s[42:43]
	global_store_dwordx4 v139, v[64:67], s[42:43] offset:16
	s_mov_b64 s[42:43], s[46:47]
	global_load_dwordx4 v[194:197], v139, s[40:41] offset:512
	global_load_dwordx4 v[198:201], v139, s[40:41] offset:528
	s_add_u32 s40, s40, 0x10000
	s_addc_u32 s41, s41, 0
	s_waitcnt vmcnt(16)
	v_pk_fma_f32 v[56:57], v[56:57], v[242:243], v[202:203]
	v_pk_fma_f32 v[58:59], v[58:59], v[244:245], v[204:205]
	v_pk_fma_f32 v[60:61], v[60:61], v[246:247], v[206:207]
	v_pk_fma_f32 v[62:63], v[62:63], v[248:249], v[208:209]
	global_store_dwordx4 v139, v[56:59], s[42:43] offset:512
	global_store_dwordx4 v139, v[60:63], s[42:43] offset:528
	s_add_u32 s42, s42, 0x10000
	s_addc_u32 s43, s43, 0
	global_load_dwordx4 v[202:205], v139, s[40:41] offset:512
	global_load_dwordx4 v[206:209], v139, s[40:41] offset:528
	s_add_u32 s40, s40, 0x10000
	s_addc_u32 s41, s41, 0
	s_waitcnt vmcnt(16)
	v_pk_fma_f32 v[52:53], v[52:53], v[242:243], v[210:211]
	v_pk_fma_f32 v[54:55], v[54:55], v[244:245], v[212:213]
	v_pk_fma_f32 v[48:49], v[48:49], v[246:247], v[214:215]
	v_pk_fma_f32 v[50:51], v[50:51], v[248:249], v[216:217]
	global_store_dwordx4 v139, v[52:55], s[42:43] offset:512
	global_store_dwordx4 v139, v[48:51], s[42:43] offset:528
	s_add_u32 s42, s42, 0x10000
	s_addc_u32 s43, s43, 0
	global_load_dwordx4 v[210:213], v139, s[40:41] offset:512
	global_load_dwordx4 v[214:217], v139, s[40:41] offset:528
	s_add_u32 s40, s40, 0x10000
	s_addc_u32 s41, s41, 0
	s_waitcnt vmcnt(16)
	v_pk_fma_f32 v[40:41], v[40:41], v[242:243], v[178:179]
	v_pk_fma_f32 v[42:43], v[42:43], v[244:245], v[180:181]
	v_pk_fma_f32 v[44:45], v[44:45], v[246:247], v[182:183]
	v_pk_fma_f32 v[46:47], v[46:47], v[248:249], v[184:185]
	global_store_dwordx4 v139, v[40:43], s[42:43] offset:512
	global_store_dwordx4 v139, v[44:47], s[42:43] offset:528
	s_add_u32 s42, s42, 0x10000
	s_addc_u32 s43, s43, 0
	global_load_dwordx4 v[178:181], v139, s[40:41] offset:512
	global_load_dwordx4 v[182:185], v139, s[40:41] offset:528
	s_waitcnt vmcnt(16)
	v_pk_fma_f32 v[32:33], v[32:33], v[242:243], v[186:187]
	v_pk_fma_f32 v[34:35], v[34:35], v[244:245], v[188:189]
	v_pk_fma_f32 v[24:25], v[24:25], v[246:247], v[190:191]
	v_pk_fma_f32 v[26:27], v[26:27], v[248:249], v[192:193]
	global_store_dwordx4 v139, v[32:35], s[42:43] offset:512
	global_store_dwordx4 v139, v[24:27], s[42:43] offset:528
	s_add_u32 s42, s42, 0x50000
	s_addc_u32 s43, s43, 0
	s_waitcnt vmcnt(14)
	v_pk_fma_f32 v[36:37], v[36:37], v[242:243], v[194:195]
	v_pk_fma_f32 v[38:39], v[38:39], v[244:245], v[196:197]
	v_pk_fma_f32 v[28:29], v[28:29], v[246:247], v[198:199]
	v_pk_fma_f32 v[30:31], v[30:31], v[248:249], v[200:201]
	global_store_dwordx4 v139, v[36:39], s[42:43] offset:512
	global_store_dwordx4 v139, v[28:31], s[42:43] offset:528
	s_add_u32 s42, s42, 0x10000
	s_addc_u32 s43, s43, 0
	s_waitcnt vmcnt(12)
	v_pk_fma_f32 v[20:21], v[20:21], v[242:243], v[202:203]
	v_pk_fma_f32 v[22:23], v[22:23], v[244:245], v[204:205]
	v_pk_fma_f32 v[16:17], v[16:17], v[246:247], v[206:207]
	v_pk_fma_f32 v[18:19], v[18:19], v[248:249], v[208:209]
	global_store_dwordx4 v139, v[20:23], s[42:43] offset:512
	global_store_dwordx4 v139, v[16:19], s[42:43] offset:528
	s_add_u32 s42, s42, 0x10000
	s_addc_u32 s43, s43, 0
	s_waitcnt vmcnt(10)
	v_pk_fma_f32 v[12:13], v[12:13], v[242:243], v[210:211]
	v_pk_fma_f32 v[14:15], v[14:15], v[244:245], v[212:213]
	v_pk_fma_f32 v[8:9], v[8:9], v[246:247], v[214:215]
	v_pk_fma_f32 v[10:11], v[10:11], v[248:249], v[216:217]
	global_store_dwordx4 v139, v[12:15], s[42:43] offset:512
	global_store_dwordx4 v139, v[8:11], s[42:43] offset:528
	s_add_u32 s42, s42, 0x10000
	s_addc_u32 s43, s43, 0
	s_waitcnt vmcnt(8)
	v_pk_fma_f32 v[4:5], v[4:5], v[242:243], v[178:179]
	v_pk_fma_f32 v[6:7], v[6:7], v[244:245], v[180:181]
	v_pk_fma_f32 v[0:1], v[0:1], v[246:247], v[182:183]
	v_pk_fma_f32 v[2:3], v[2:3], v[248:249], v[184:185]
	global_store_dwordx4 v139, v[4:7], s[42:43] offset:512
	global_store_dwordx4 v139, v[0:3], s[42:43] offset:528
	v_pk_mul_f32 v[200:201], v[128:129], v[128:129]
	v_pk_mul_f32 v[202:203], v[124:125], v[124:125]
	v_pk_mul_f32 v[204:205], v[112:113], v[112:113]
	v_pk_mul_f32 v[206:207], v[100:101], v[100:101]
	v_pk_mul_f32 v[208:209], v[104:105], v[104:105]
	v_pk_mul_f32 v[210:211], v[92:93], v[92:93]
	v_pk_mul_f32 v[212:213], v[72:73], v[72:73]
	v_pk_mul_f32 v[214:215], v[68:69], v[68:69]
	v_pk_fma_f32 v[200:201], v[130:131], v[130:131], v[200:201]
	v_pk_fma_f32 v[202:203], v[126:127], v[126:127], v[202:203]
	v_pk_fma_f32 v[204:205], v[114:115], v[114:115], v[204:205]
	v_pk_fma_f32 v[206:207], v[102:103], v[102:103], v[206:207]
	v_pk_fma_f32 v[208:209], v[106:107], v[106:107], v[208:209]
	v_pk_fma_f32 v[210:211], v[94:95], v[94:95], v[210:211]
	v_pk_fma_f32 v[212:213], v[74:75], v[74:75], v[212:213]
	v_pk_fma_f32 v[214:215], v[70:71], v[70:71], v[214:215]
	v_pk_fma_f32 v[200:201], v[132:133], v[132:133], v[200:201]
	v_pk_fma_f32 v[202:203], v[120:121], v[120:121], v[202:203]
	v_pk_fma_f32 v[204:205], v[116:117], v[116:117], v[204:205]
	v_pk_fma_f32 v[206:207], v[96:97], v[96:97], v[206:207]
	v_pk_fma_f32 v[208:209], v[108:109], v[108:109], v[208:209]
	v_pk_fma_f32 v[210:211], v[84:85], v[84:85], v[210:211]
	v_pk_fma_f32 v[212:213], v[76:77], v[76:77], v[212:213]
	v_pk_fma_f32 v[214:215], v[64:65], v[64:65], v[214:215]
	v_pk_fma_f32 v[200:201], v[134:135], v[134:135], v[200:201]
	v_pk_fma_f32 v[202:203], v[122:123], v[122:123], v[202:203]
	v_pk_fma_f32 v[204:205], v[118:119], v[118:119], v[204:205]
	v_pk_fma_f32 v[206:207], v[98:99], v[98:99], v[206:207]
	v_pk_fma_f32 v[208:209], v[110:111], v[110:111], v[208:209]
	v_pk_fma_f32 v[210:211], v[86:87], v[86:87], v[210:211]
	v_pk_fma_f32 v[212:213], v[78:79], v[78:79], v[212:213]
	v_pk_fma_f32 v[214:215], v[66:67], v[66:67], v[214:215]
	v_pk_fma_f32 v[200:201], v[56:57], v[56:57], v[200:201]
	v_pk_fma_f32 v[202:203], v[52:53], v[52:53], v[202:203]
	v_pk_fma_f32 v[204:205], v[40:41], v[40:41], v[204:205]
	v_pk_fma_f32 v[206:207], v[32:33], v[32:33], v[206:207]
	v_pk_fma_f32 v[208:209], v[36:37], v[36:37], v[208:209]
	v_pk_fma_f32 v[210:211], v[20:21], v[20:21], v[210:211]
	v_pk_fma_f32 v[212:213], v[12:13], v[12:13], v[212:213]
	v_pk_fma_f32 v[214:215], v[4:5], v[4:5], v[214:215]
	v_pk_fma_f32 v[200:201], v[58:59], v[58:59], v[200:201]
	v_pk_fma_f32 v[202:203], v[54:55], v[54:55], v[202:203]
	v_pk_fma_f32 v[204:205], v[42:43], v[42:43], v[204:205]
	v_pk_fma_f32 v[206:207], v[34:35], v[34:35], v[206:207]
	v_pk_fma_f32 v[208:209], v[38:39], v[38:39], v[208:209]
	v_pk_fma_f32 v[210:211], v[22:23], v[22:23], v[210:211]
	v_pk_fma_f32 v[212:213], v[14:15], v[14:15], v[212:213]
	v_pk_fma_f32 v[214:215], v[6:7], v[6:7], v[214:215]
	v_pk_fma_f32 v[200:201], v[60:61], v[60:61], v[200:201]
	v_pk_fma_f32 v[202:203], v[48:49], v[48:49], v[202:203]
	v_pk_fma_f32 v[204:205], v[44:45], v[44:45], v[204:205]
	v_pk_fma_f32 v[206:207], v[24:25], v[24:25], v[206:207]
	v_pk_fma_f32 v[208:209], v[28:29], v[28:29], v[208:209]
	v_pk_fma_f32 v[210:211], v[16:17], v[16:17], v[210:211]
	v_pk_fma_f32 v[212:213], v[8:9], v[8:9], v[212:213]
	v_pk_fma_f32 v[214:215], v[0:1], v[0:1], v[214:215]
	v_pk_fma_f32 v[200:201], v[62:63], v[62:63], v[200:201]
	v_pk_fma_f32 v[202:203], v[50:51], v[50:51], v[202:203]
	v_pk_fma_f32 v[204:205], v[46:47], v[46:47], v[204:205]
	v_pk_fma_f32 v[206:207], v[26:27], v[26:27], v[206:207]
	v_pk_fma_f32 v[208:209], v[30:31], v[30:31], v[208:209]
	v_pk_fma_f32 v[210:211], v[18:19], v[18:19], v[210:211]
	v_pk_fma_f32 v[212:213], v[10:11], v[10:11], v[212:213]
	v_pk_fma_f32 v[214:215], v[2:3], v[2:3], v[214:215]
	v_add_f32_e32 v216, v200, v201
	v_add_f32_e32 v217, v202, v203
	v_add_f32_e32 v218, v204, v205
	v_add_f32_e32 v219, v206, v207
	v_add_f32_e32 v220, v208, v209
	v_add_f32_e32 v221, v210, v211
	v_add_f32_e32 v222, v212, v213
	v_add_f32_e32 v223, v214, v215
	v_and_b32_e32 v224, 63, v154
	v_xor_b32_e32 v225, 32, v224
	v_xor_b32_e32 v224, 16, v224
	v_lshlrev_b32_e32 v224, 2, v224
	v_lshlrev_b32_e32 v225, 2, v225
	ds_bpermute_b32 v226, v224, v216
	ds_bpermute_b32 v227, v224, v217
	ds_bpermute_b32 v228, v224, v218
	ds_bpermute_b32 v229, v224, v219
	ds_bpermute_b32 v230, v224, v220
	ds_bpermute_b32 v231, v224, v221
	ds_bpermute_b32 v232, v224, v222
	ds_bpermute_b32 v233, v224, v223
	s_waitcnt lgkmcnt(0)
	v_add_f32_e32 v216, v216, v226
	v_add_f32_e32 v217, v217, v227
	v_add_f32_e32 v218, v218, v228
	v_add_f32_e32 v219, v219, v229
	v_add_f32_e32 v220, v220, v230
	v_add_f32_e32 v221, v221, v231
	v_add_f32_e32 v222, v222, v232
	v_add_f32_e32 v223, v223, v233
	ds_bpermute_b32 v226, v225, v216
	ds_bpermute_b32 v227, v225, v217
	ds_bpermute_b32 v228, v225, v218
	ds_bpermute_b32 v229, v225, v219
	ds_bpermute_b32 v230, v225, v220
	ds_bpermute_b32 v231, v225, v221
	ds_bpermute_b32 v232, v225, v222
	ds_bpermute_b32 v233, v225, v223
	s_waitcnt lgkmcnt(0)
	v_add_f32_e32 v216, v216, v226
	v_add_f32_e32 v217, v217, v227
	v_add_f32_e32 v218, v218, v228
	v_add_f32_e32 v219, v219, v229
	v_add_f32_e32 v220, v220, v230
	v_add_f32_e32 v221, v221, v231
	v_add_f32_e32 v222, v222, v232
	v_add_f32_e32 v223, v223, v233
	v_bfe_u32 v234, v154, 6, 2
	v_lshlrev_b32_e32 v234, 8, v234
	v_lshrrev_b32_e32 v235, 8, v154
	v_lshl_add_u32 v234, v235, 6, v234
	v_and_b32_e32 v235, 15, v154
	v_add_u32_e32 v234, v234, v235
	v_lshlrev_b32_e32 v234, 2, v234
	ds_write_b32 v234, v216 offset:0
	ds_write_b32 v234, v217 offset:64
	ds_write_b32 v234, v218 offset:128
	ds_write_b32 v234, v219 offset:192
	ds_write_b32 v234, v220 offset:512
	ds_write_b32 v234, v221 offset:576
	ds_write_b32 v234, v222 offset:640
	ds_write_b32 v234, v223 offset:704
	s_waitcnt lgkmcnt(0)
	s_barrier
	v_cmp_gt_u32_e32 vcc, 0x100, v154
	s_and_saveexec_b64 s[48:49], vcc
	v_lshlrev_b32_e32 v235, 2, v154
	ds_read_b32 v236, v235
	ds_read_b32 v237, v235 offset:1024
	ds_read_b32 v238, v235 offset:2048
	ds_read_b32 v239, v235 offset:3072
	s_lshl_b32 s50, s8, 3
	s_and_b32 s50, s50, 56
	s_bfe_u32 s51, s8, 0x30003
	s_or_b32 s50, s50, s51
	s_lshl_b32 s50, s50, 2
	s_lshr_b32 s51, s8, 6
	s_or_b32 s50, s50, s51
	s_lshl_b32 s50, s50, 10
	s_add_u32 s50, s50, s72
	s_addc_u32 s51, s73, 0
	s_add_u32 s50, s50, 0x19500000
	s_addc_u32 s51, s51, 0
	s_waitcnt lgkmcnt(0)
	v_add_f32_e32 v236, v236, v237
	v_add_f32_e32 v238, v238, v239
	v_add_f32_e32 v236, v236, v238
	global_store_dword v235, v236, s[50:51]
	s_mov_b64 exec, s[48:49]
	s_mov_b32 s92, s8
	v_mov_b64_e32 v[242:243], v[0:1]
	v_mov_b64_e32 v[244:245], v[2:3]
	v_mov_b64_e32 v[246:247], v[4:5]
	v_mov_b64_e32 v[248:249], v[6:7]
	s_add_i32 s8, s8, s74
	s_add_i32 s13, s13, s20
	s_cmpk_lt_i32 s8, 0x100
	s_cbranch_scc0 .LBB0_594

.LBB0_698:
	s_or_b64 exec, exec, s[0:1]
	v_mov_b32_e32 v80, v154
	s_lshr_b32 s1, s10, 3
	v_and_b32_e32 v136, 15, v80
	v_lshrrev_b32_e32 v81, 1, v80
	v_ashrrev_i32_e32 v80, 2, v80
	s_lshl_b32 s0, s12, 8
	s_mul_i32 s1, s1, 0x9000
	v_and_b32_e32 v152, 0xffffffc0, v80
	v_and_b32_e32 v81, 0x78, v81
	s_add_u32 s10, s7, s1
	v_ashrrev_i32_e32 v153, 31, v152
	s_mov_b32 s1, s52
	v_lshl_or_b32 v144, s11, 8, v81
	v_lshl_add_u64 v[140:141], v[152:153], 0, s[0:1]
	v_ashrrev_i32_e32 v145, 31, v144
	v_or_b32_e32 v140, v140, v136
	s_addc_u32 s11, s8, 0
	v_lshlrev_b64 v[150:151], 2, v[144:145]
	v_lshlrev_b64 v[140:141], 12, v[140:141]
	v_lshl_add_u64 v[148:149], s[10:11], 0, v[150:151]
	v_lshl_add_u64 v[170:171], s[70:71], 0, v[140:141]
	v_lshl_add_u64 v[146:147], v[170:171], 0, v[150:151]
	s_nop 1
	v_readfirstlane_b32 s38, v146
	v_readfirstlane_b32 s39, v147
	s_nop 1
	v_subrev_u32_e32 v139, s38, v146
	s_mov_b64 s[40:41], s[38:39]
	s_mov_b64 s[42:43], s[38:39]
	s_mov_b64 s[44:45], s[40:41]
	s_mov_b64 s[46:47], s[42:43]
	global_load_dwordx4 v[234:237], v[148:149], off
	global_load_dwordx4 v[238:241], v[148:149], off offset:16
	global_load_dwordx4 v[242:245], v[148:149], off offset:512
	global_load_dwordx4 v[246:249], v[148:149], off offset:528
	global_load_dwordx4 v[178:181], v139, s[40:41]
	global_load_dwordx4 v[182:185], v139, s[40:41] offset:16
	s_add_u32 s40, s40, 0x10000
	s_addc_u32 s41, s41, 0
	global_load_dwordx4 v[186:189], v139, s[40:41]
	global_load_dwordx4 v[190:193], v139, s[40:41] offset:16
	s_add_u32 s40, s40, 0x10000
	s_addc_u32 s41, s41, 0
	global_load_dwordx4 v[194:197], v139, s[40:41]
	global_load_dwordx4 v[198:201], v139, s[40:41] offset:16
	s_add_u32 s40, s40, 0x10000
	s_addc_u32 s41, s41, 0
	global_load_dwordx4 v[202:205], v139, s[40:41]
	global_load_dwordx4 v[206:209], v139, s[40:41] offset:16
	s_add_u32 s40, s40, 0x50000
	s_addc_u32 s41, s41, 0
	global_load_dwordx4 v[210:213], v139, s[40:41]
	global_load_dwordx4 v[214:217], v139, s[40:41] offset:16
	s_add_u32 s40, s40, 0x10000
	s_addc_u32 s41, s41, 0
	s_waitcnt vmcnt(8)
	v_pk_mul_f32 v[132:133], v[132:133], v[234:235]
	v_pk_mul_f32 v[134:135], v[134:135], v[236:237]
	v_pk_mul_f32 v[128:129], v[128:129], v[238:239]
	v_pk_mul_f32 v[130:131], v[130:131], v[240:241]
	v_pk_fma_f32 v[132:133], v[132:133], 0.5, v[178:179] op_sel_hi:[1,0,1]
	v_pk_fma_f32 v[134:135], v[134:135], 0.5, v[180:181] op_sel_hi:[1,0,1]
	v_pk_fma_f32 v[128:129], v[128:129], 0.5, v[182:183] op_sel_hi:[1,0,1]
	v_pk_fma_f32 v[130:131], v[130:131], 0.5, v[184:185] op_sel_hi:[1,0,1]
	global_store_dwordx4 v139, v[132:135], s[42:43]
	global_store_dwordx4 v139, v[128:131], s[42:43] offset:16
	s_add_u32 s42, s42, 0x10000
	s_addc_u32 s43, s43, 0
	global_load_dwordx4 v[178:181], v139, s[40:41]
	global_load_dwordx4 v[182:185], v139, s[40:41] offset:16
	s_add_u32 s40, s40, 0x10000
	s_addc_u32 s41, s41, 0
	s_waitcnt vmcnt(10)
	v_pk_mul_f32 v[124:125], v[124:125], v[234:235]
	v_pk_mul_f32 v[126:127], v[126:127], v[236:237]
	v_pk_mul_f32 v[120:121], v[120:121], v[238:239]
	v_pk_mul_f32 v[122:123], v[122:123], v[240:241]
	v_pk_fma_f32 v[124:125], v[124:125], 0.5, v[186:187] op_sel_hi:[1,0,1]
	v_pk_fma_f32 v[126:127], v[126:127], 0.5, v[188:189] op_sel_hi:[1,0,1]
	v_pk_fma_f32 v[120:121], v[120:121], 0.5, v[190:191] op_sel_hi:[1,0,1]
	v_pk_fma_f32 v[122:123], v[122:123], 0.5, v[192:193] op_sel_hi:[1,0,1]
	global_store_dwordx4 v139, v[124:127], s[42:43]
	global_store_dwordx4 v139, v[120:123], s[42:43] offset:16
	s_add_u32 s42, s42, 0x10000
	s_addc_u32 s43, s43, 0
	global_load_dwordx4 v[186:189], v139, s[40:41]
	global_load_dwordx4 v[190:193], v139, s[40:41] offset:16
	s_add_u32 s40, s40, 0x10000
	s_addc_u32 s41, s41, 0
	s_waitcnt vmcnt(12)
	v_pk_mul_f32 v[116:117], v[116:117], v[234:235]
	v_pk_mul_f32 v[118:119], v[118:119], v[236:237]
	v_pk_mul_f32 v[112:113], v[112:113], v[238:239]
	v_pk_mul_f32 v[114:115], v[114:115], v[240:241]
	v_pk_fma_f32 v[116:117], v[116:117], 0.5, v[194:195] op_sel_hi:[1,0,1]
	v_pk_fma_f32 v[118:119], v[118:119], 0.5, v[196:197] op_sel_hi:[1,0,1]
	v_pk_fma_f32 v[112:113], v[112:113], 0.5, v[198:199] op_sel_hi:[1,0,1]
	v_pk_fma_f32 v[114:115], v[114:115], 0.5, v[200:201] op_sel_hi:[1,0,1]
	global_store_dwordx4 v139, v[116:119], s[42:43]
	global_store_dwordx4 v139, v[112:115], s[42:43] offset:16
	s_add_u32 s42, s42, 0x10000
	s_addc_u32 s43, s43, 0
	global_load_dwordx4 v[194:197], v139, s[40:41]
	global_load_dwordx4 v[198:201], v139, s[40:41] offset:16
	s_mov_b64 s[40:41], s[44:45]
	s_waitcnt vmcnt(14)
	v_pk_mul_f32 v[108:109], v[108:109], v[234:235]
	v_pk_mul_f32 v[110:111], v[110:111], v[236:237]
	v_pk_mul_f32 v[104:105], v[104:105], v[238:239]
	v_pk_mul_f32 v[106:107], v[106:107], v[240:241]
	v_pk_fma_f32 v[108:109], v[108:109], 0.5, v[202:203] op_sel_hi:[1,0,1]
	v_pk_fma_f32 v[110:111], v[110:111], 0.5, v[204:205] op_sel_hi:[1,0,1]
	v_pk_fma_f32 v[104:105], v[104:105], 0.5, v[206:207] op_sel_hi:[1,0,1]
	v_pk_fma_f32 v[106:107], v[106:107], 0.5, v[208:209] op_sel_hi:[1,0,1]
	global_store_dwordx4 v139, v[108:111], s[42:43]
	global_store_dwordx4 v139, v[104:107], s[42:43] offset:16
	s_add_u32 s42, s42, 0x50000
	s_addc_u32 s43, s43, 0
	global_load_dwordx4 v[202:205], v139, s[40:41] offset:512
	global_load_dwordx4 v[206:209], v139, s[40:41] offset:528
	s_add_u32 s40, s40, 0x10000
	s_addc_u32 s41, s41, 0
	s_waitcnt vmcnt(16)
	v_pk_mul_f32 v[100:101], v[100:101], v[234:235]
	v_pk_mul_f32 v[102:103], v[102:103], v[236:237]
	v_pk_mul_f32 v[96:97], v[96:97], v[238:239]
	v_pk_mul_f32 v[98:99], v[98:99], v[240:241]
	v_pk_fma_f32 v[100:101], v[100:101], 0.5, v[210:211] op_sel_hi:[1,0,1]
	v_pk_fma_f32 v[102:103], v[102:103], 0.5, v[212:213] op_sel_hi:[1,0,1]
	v_pk_fma_f32 v[96:97], v[96:97], 0.5, v[214:215] op_sel_hi:[1,0,1]
	v_pk_fma_f32 v[98:99], v[98:99], 0.5, v[216:217] op_sel_hi:[1,0,1]
	global_store_dwordx4 v139, v[100:103], s[42:43]
	global_store_dwordx4 v139, v[96:99], s[42:43] offset:16
	s_add_u32 s42, s42, 0x10000
	s_addc_u32 s43, s43, 0
	global_load_dwordx4 v[210:213], v139, s[40:41] offset:512
	global_load_dwordx4 v[214:217], v139, s[40:41] offset:528
	s_add_u32 s40, s40, 0x10000
	s_addc_u32 s41, s41, 0
	s_waitcnt vmcnt(16)
	v_pk_mul_f32 v[92:93], v[92:93], v[234:235]
	v_pk_mul_f32 v[94:95], v[94:95], v[236:237]
	v_pk_mul_f32 v[88:89], v[88:89], v[238:239]
	v_pk_mul_f32 v[90:91], v[90:91], v[240:241]
	v_pk_fma_f32 v[92:93], v[92:93], 0.5, v[178:179] op_sel_hi:[1,0,1]
	v_pk_fma_f32 v[94:95], v[94:95], 0.5, v[180:181] op_sel_hi:[1,0,1]
	v_pk_fma_f32 v[88:89], v[88:89], 0.5, v[182:183] op_sel_hi:[1,0,1]
	v_pk_fma_f32 v[90:91], v[90:91], 0.5, v[184:185] op_sel_hi:[1,0,1]
	global_store_dwordx4 v139, v[92:95], s[42:43]
	global_store_dwordx4 v139, v[88:91], s[42:43] offset:16
	s_add_u32 s42, s42, 0x10000
	s_addc_u32 s43, s43, 0
	global_load_dwordx4 v[178:181], v139, s[40:41] offset:512
	global_load_dwordx4 v[182:185], v139, s[40:41] offset:528
	s_add_u32 s40, s40, 0x10000
	s_addc_u32 s41, s41, 0
	s_waitcnt vmcnt(16)
	v_pk_mul_f32 v[76:77], v[76:77], v[234:235]
	v_pk_mul_f32 v[78:79], v[78:79], v[236:237]
	v_pk_mul_f32 v[72:73], v[72:73], v[238:239]
	v_pk_mul_f32 v[74:75], v[74:75], v[240:241]
	v_pk_fma_f32 v[76:77], v[76:77], 0.5, v[186:187] op_sel_hi:[1,0,1]
	v_pk_fma_f32 v[78:79], v[78:79], 0.5, v[188:189] op_sel_hi:[1,0,1]
	v_pk_fma_f32 v[72:73], v[72:73], 0.5, v[190:191] op_sel_hi:[1,0,1]
	v_pk_fma_f32 v[74:75], v[74:75], 0.5, v[192:193] op_sel_hi:[1,0,1]
	global_store_dwordx4 v139, v[76:79], s[42:43]
	global_store_dwordx4 v139, v[72:75], s[42:43] offset:16
	s_add_u32 s42, s42, 0x10000
	s_addc_u32 s43, s43, 0
	global_load_dwordx4 v[186:189], v139, s[40:41] offset:512
	global_load_dwordx4 v[190:193], v139, s[40:41] offset:528
	s_add_u32 s40, s40, 0x50000
	s_addc_u32 s41, s41, 0
	s_waitcnt vmcnt(16)
	v_pk_mul_f32 v[68:69], v[68:69], v[234:235]
	v_pk_mul_f32 v[70:71], v[70:71], v[236:237]
	v_pk_mul_f32 v[64:65], v[64:65], v[238:239]
	v_pk_mul_f32 v[66:67], v[66:67], v[240:241]
	v_pk_fma_f32 v[68:69], v[68:69], 0.5, v[194:195] op_sel_hi:[1,0,1]
	v_pk_fma_f32 v[70:71], v[70:71], 0.5, v[196:197] op_sel_hi:[1,0,1]
	v_pk_fma_f32 v[64:65], v[64:65], 0.5, v[198:199] op_sel_hi:[1,0,1]
	v_pk_fma_f32 v[66:67], v[66:67], 0.5, v[200:201] op_sel_hi:[1,0,1]
	global_store_dwordx4 v139, v[68:71], s[42:43]
	global_store_dwordx4 v139, v[64:67], s[42:43] offset:16
	s_mov_b64 s[42:43], s[46:47]
	global_load_dwordx4 v[194:197], v139, s[40:41] offset:512
	global_load_dwordx4 v[198:201], v139, s[40:41] offset:528
	s_add_u32 s40, s40, 0x10000
	s_addc_u32 s41, s41, 0
	s_waitcnt vmcnt(16)
	v_pk_mul_f32 v[60:61], v[60:61], v[242:243]
	v_pk_mul_f32 v[62:63], v[62:63], v[244:245]
	v_pk_mul_f32 v[56:57], v[56:57], v[246:247]
	v_pk_mul_f32 v[58:59], v[58:59], v[248:249]
	v_pk_fma_f32 v[60:61], v[60:61], 0.5, v[202:203] op_sel_hi:[1,0,1]
	v_pk_fma_f32 v[62:63], v[62:63], 0.5, v[204:205] op_sel_hi:[1,0,1]
	v_pk_fma_f32 v[56:57], v[56:57], 0.5, v[206:207] op_sel_hi:[1,0,1]
	v_pk_fma_f32 v[58:59], v[58:59], 0.5, v[208:209] op_sel_hi:[1,0,1]
	global_store_dwordx4 v139, v[60:63], s[42:43] offset:512
	global_store_dwordx4 v139, v[56:59], s[42:43] offset:528
	s_add_u32 s42, s42, 0x10000
	s_addc_u32 s43, s43, 0
	global_load_dwordx4 v[202:205], v139, s[40:41] offset:512
	global_load_dwordx4 v[206:209], v139, s[40:41] offset:528
	s_add_u32 s40, s40, 0x10000
	s_addc_u32 s41, s41, 0
	s_waitcnt vmcnt(16)
	v_pk_mul_f32 v[52:53], v[52:53], v[242:243]
	v_pk_mul_f32 v[54:55], v[54:55], v[244:245]
	v_pk_mul_f32 v[48:49], v[48:49], v[246:247]
	v_pk_mul_f32 v[50:51], v[50:51], v[248:249]
	v_pk_fma_f32 v[52:53], v[52:53], 0.5, v[210:211] op_sel_hi:[1,0,1]
	v_pk_fma_f32 v[54:55], v[54:55], 0.5, v[212:213] op_sel_hi:[1,0,1]
	v_pk_fma_f32 v[48:49], v[48:49], 0.5, v[214:215] op_sel_hi:[1,0,1]
	v_pk_fma_f32 v[50:51], v[50:51], 0.5, v[216:217] op_sel_hi:[1,0,1]
	global_store_dwordx4 v139, v[52:55], s[42:43] offset:512
	global_store_dwordx4 v139, v[48:51], s[42:43] offset:528
	s_add_u32 s42, s42, 0x10000
	s_addc_u32 s43, s43, 0
	global_load_dwordx4 v[210:213], v139, s[40:41] offset:512
	global_load_dwordx4 v[214:217], v139, s[40:41] offset:528
	s_add_u32 s40, s40, 0x10000
	s_addc_u32 s41, s41, 0
	s_waitcnt vmcnt(16)
	v_pk_mul_f32 v[44:45], v[44:45], v[242:243]
	v_pk_mul_f32 v[46:47], v[46:47], v[244:245]
	v_pk_mul_f32 v[40:41], v[40:41], v[246:247]
	v_pk_mul_f32 v[42:43], v[42:43], v[248:249]
	v_pk_fma_f32 v[44:45], v[44:45], 0.5, v[178:179] op_sel_hi:[1,0,1]
	v_pk_fma_f32 v[46:47], v[46:47], 0.5, v[180:181] op_sel_hi:[1,0,1]
	v_pk_fma_f32 v[40:41], v[40:41], 0.5, v[182:183] op_sel_hi:[1,0,1]
	v_pk_fma_f32 v[42:43], v[42:43], 0.5, v[184:185] op_sel_hi:[1,0,1]
	global_store_dwordx4 v139, v[44:47], s[42:43] offset:512
	global_store_dwordx4 v139, v[40:43], s[42:43] offset:528
	s_add_u32 s42, s42, 0x10000
	s_addc_u32 s43, s43, 0
	global_load_dwordx4 v[178:181], v139, s[40:41] offset:512
	global_load_dwordx4 v[182:185], v139, s[40:41] offset:528
	s_waitcnt vmcnt(16)
	v_pk_mul_f32 v[36:37], v[36:37], v[242:243]
	v_pk_mul_f32 v[38:39], v[38:39], v[244:245]
	v_pk_mul_f32 v[32:33], v[32:33], v[246:247]
	v_pk_mul_f32 v[34:35], v[34:35], v[248:249]
	v_pk_fma_f32 v[36:37], v[36:37], 0.5, v[186:187] op_sel_hi:[1,0,1]
	v_pk_fma_f32 v[38:39], v[38:39], 0.5, v[188:189] op_sel_hi:[1,0,1]
	v_pk_fma_f32 v[32:33], v[32:33], 0.5, v[190:191] op_sel_hi:[1,0,1]
	v_pk_fma_f32 v[34:35], v[34:35], 0.5, v[192:193] op_sel_hi:[1,0,1]
	global_store_dwordx4 v139, v[36:39], s[42:43] offset:512
	global_store_dwordx4 v139, v[32:35], s[42:43] offset:528
	s_add_u32 s42, s42, 0x50000
	s_addc_u32 s43, s43, 0
	s_waitcnt vmcnt(14)
	v_pk_mul_f32 v[28:29], v[28:29], v[242:243]
	v_pk_mul_f32 v[30:31], v[30:31], v[244:245]
	v_pk_mul_f32 v[24:25], v[24:25], v[246:247]
	v_pk_mul_f32 v[26:27], v[26:27], v[248:249]
	v_pk_fma_f32 v[28:29], v[28:29], 0.5, v[194:195] op_sel_hi:[1,0,1]
	v_pk_fma_f32 v[30:31], v[30:31], 0.5, v[196:197] op_sel_hi:[1,0,1]
	v_pk_fma_f32 v[24:25], v[24:25], 0.5, v[198:199] op_sel_hi:[1,0,1]
	v_pk_fma_f32 v[26:27], v[26:27], 0.5, v[200:201] op_sel_hi:[1,0,1]
	global_store_dwordx4 v139, v[28:31], s[42:43] offset:512
	global_store_dwordx4 v139, v[24:27], s[42:43] offset:528
	s_add_u32 s42, s42, 0x10000
	s_addc_u32 s43, s43, 0
	s_waitcnt vmcnt(12)
	v_pk_mul_f32 v[20:21], v[20:21], v[242:243]
	v_pk_mul_f32 v[22:23], v[22:23], v[244:245]
	v_pk_mul_f32 v[16:17], v[16:17], v[246:247]
	v_pk_mul_f32 v[18:19], v[18:19], v[248:249]
	v_pk_fma_f32 v[20:21], v[20:21], 0.5, v[202:203] op_sel_hi:[1,0,1]
	v_pk_fma_f32 v[22:23], v[22:23], 0.5, v[204:205] op_sel_hi:[1,0,1]
	v_pk_fma_f32 v[16:17], v[16:17], 0.5, v[206:207] op_sel_hi:[1,0,1]
	v_pk_fma_f32 v[18:19], v[18:19], 0.5, v[208:209] op_sel_hi:[1,0,1]
	global_store_dwordx4 v139, v[20:23], s[42:43] offset:512
	global_store_dwordx4 v139, v[16:19], s[42:43] offset:528
	s_add_u32 s42, s42, 0x10000
	s_addc_u32 s43, s43, 0
	s_waitcnt vmcnt(10)
	v_pk_mul_f32 v[12:13], v[12:13], v[242:243]
	v_pk_mul_f32 v[14:15], v[14:15], v[244:245]
	v_pk_mul_f32 v[8:9], v[8:9], v[246:247]
	v_pk_mul_f32 v[10:11], v[10:11], v[248:249]
	v_pk_fma_f32 v[12:13], v[12:13], 0.5, v[210:211] op_sel_hi:[1,0,1]
	v_pk_fma_f32 v[14:15], v[14:15], 0.5, v[212:213] op_sel_hi:[1,0,1]
	v_pk_fma_f32 v[8:9], v[8:9], 0.5, v[214:215] op_sel_hi:[1,0,1]
	v_pk_fma_f32 v[10:11], v[10:11], 0.5, v[216:217] op_sel_hi:[1,0,1]
	global_store_dwordx4 v139, v[12:15], s[42:43] offset:512
	global_store_dwordx4 v139, v[8:11], s[42:43] offset:528
	s_add_u32 s42, s42, 0x10000
	s_addc_u32 s43, s43, 0
	s_waitcnt vmcnt(8)
	v_pk_mul_f32 v[4:5], v[4:5], v[242:243]
	v_pk_mul_f32 v[6:7], v[6:7], v[244:245]
	v_pk_mul_f32 v[0:1], v[0:1], v[246:247]
	v_pk_mul_f32 v[2:3], v[2:3], v[248:249]
	v_pk_fma_f32 v[4:5], v[4:5], 0.5, v[178:179] op_sel_hi:[1,0,1]
	v_pk_fma_f32 v[6:7], v[6:7], 0.5, v[180:181] op_sel_hi:[1,0,1]
	v_pk_fma_f32 v[0:1], v[0:1], 0.5, v[182:183] op_sel_hi:[1,0,1]
	v_pk_fma_f32 v[2:3], v[2:3], 0.5, v[184:185] op_sel_hi:[1,0,1]
	global_store_dwordx4 v139, v[4:7], s[42:43] offset:512
	global_store_dwordx4 v139, v[0:3], s[42:43] offset:528
	v_pk_mul_f32 v[200:201], v[132:133], v[132:133]
	v_pk_mul_f32 v[202:203], v[124:125], v[124:125]
	v_pk_mul_f32 v[204:205], v[116:117], v[116:117]
	v_pk_mul_f32 v[206:207], v[108:109], v[108:109]
	v_pk_mul_f32 v[208:209], v[100:101], v[100:101]
	v_pk_mul_f32 v[210:211], v[92:93], v[92:93]
	v_pk_mul_f32 v[212:213], v[76:77], v[76:77]
	v_pk_mul_f32 v[214:215], v[68:69], v[68:69]
	v_pk_fma_f32 v[200:201], v[134:135], v[134:135], v[200:201]
	v_pk_fma_f32 v[202:203], v[126:127], v[126:127], v[202:203]
	v_pk_fma_f32 v[204:205], v[118:119], v[118:119], v[204:205]
	v_pk_fma_f32 v[206:207], v[110:111], v[110:111], v[206:207]
	v_pk_fma_f32 v[208:209], v[102:103], v[102:103], v[208:209]
	v_pk_fma_f32 v[210:211], v[94:95], v[94:95], v[210:211]
	v_pk_fma_f32 v[212:213], v[78:79], v[78:79], v[212:213]
	v_pk_fma_f32 v[214:215], v[70:71], v[70:71], v[214:215]
	v_pk_fma_f32 v[200:201], v[128:129], v[128:129], v[200:201]
	v_pk_fma_f32 v[202:203], v[120:121], v[120:121], v[202:203]
	v_pk_fma_f32 v[204:205], v[112:113], v[112:113], v[204:205]
	v_pk_fma_f32 v[206:207], v[104:105], v[104:105], v[206:207]
	v_pk_fma_f32 v[208:209], v[96:97], v[96:97], v[208:209]
	v_pk_fma_f32 v[210:211], v[88:89], v[88:89], v[210:211]
	v_pk_fma_f32 v[212:213], v[72:73], v[72:73], v[212:213]
	v_pk_fma_f32 v[214:215], v[64:65], v[64:65], v[214:215]
	v_pk_fma_f32 v[200:201], v[130:131], v[130:131], v[200:201]
	v_pk_fma_f32 v[202:203], v[122:123], v[122:123], v[202:203]
	v_pk_fma_f32 v[204:205], v[114:115], v[114:115], v[204:205]
	v_pk_fma_f32 v[206:207], v[106:107], v[106:107], v[206:207]
	v_pk_fma_f32 v[208:209], v[98:99], v[98:99], v[208:209]
	v_pk_fma_f32 v[210:211], v[90:91], v[90:91], v[210:211]
	v_pk_fma_f32 v[212:213], v[74:75], v[74:75], v[212:213]
	v_pk_fma_f32 v[214:215], v[66:67], v[66:67], v[214:215]
	v_pk_fma_f32 v[200:201], v[60:61], v[60:61], v[200:201]
	v_pk_fma_f32 v[202:203], v[52:53], v[52:53], v[202:203]
	v_pk_fma_f32 v[204:205], v[44:45], v[44:45], v[204:205]
	v_pk_fma_f32 v[206:207], v[36:37], v[36:37], v[206:207]
	v_pk_fma_f32 v[208:209], v[28:29], v[28:29], v[208:209]
	v_pk_fma_f32 v[210:211], v[20:21], v[20:21], v[210:211]
	v_pk_fma_f32 v[212:213], v[12:13], v[12:13], v[212:213]
	v_pk_fma_f32 v[214:215], v[4:5], v[4:5], v[214:215]
	v_pk_fma_f32 v[200:201], v[62:63], v[62:63], v[200:201]
	v_pk_fma_f32 v[202:203], v[54:55], v[54:55], v[202:203]
	v_pk_fma_f32 v[204:205], v[46:47], v[46:47], v[204:205]
	v_pk_fma_f32 v[206:207], v[38:39], v[38:39], v[206:207]
	v_pk_fma_f32 v[208:209], v[30:31], v[30:31], v[208:209]
	v_pk_fma_f32 v[210:211], v[22:23], v[22:23], v[210:211]
	v_pk_fma_f32 v[212:213], v[14:15], v[14:15], v[212:213]
	v_pk_fma_f32 v[214:215], v[6:7], v[6:7], v[214:215]
	v_pk_fma_f32 v[200:201], v[56:57], v[56:57], v[200:201]
	v_pk_fma_f32 v[202:203], v[48:49], v[48:49], v[202:203]
	v_pk_fma_f32 v[204:205], v[40:41], v[40:41], v[204:205]
	v_pk_fma_f32 v[206:207], v[32:33], v[32:33], v[206:207]
	v_pk_fma_f32 v[208:209], v[24:25], v[24:25], v[208:209]
	v_pk_fma_f32 v[210:211], v[16:17], v[16:17], v[210:211]
	v_pk_fma_f32 v[212:213], v[8:9], v[8:9], v[212:213]
	v_pk_fma_f32 v[214:215], v[0:1], v[0:1], v[214:215]
	v_pk_fma_f32 v[200:201], v[58:59], v[58:59], v[200:201]
	v_pk_fma_f32 v[202:203], v[50:51], v[50:51], v[202:203]
	v_pk_fma_f32 v[204:205], v[42:43], v[42:43], v[204:205]
	v_pk_fma_f32 v[206:207], v[34:35], v[34:35], v[206:207]
	v_pk_fma_f32 v[208:209], v[26:27], v[26:27], v[208:209]
	v_pk_fma_f32 v[210:211], v[18:19], v[18:19], v[210:211]
	v_pk_fma_f32 v[212:213], v[10:11], v[10:11], v[212:213]
	v_pk_fma_f32 v[214:215], v[2:3], v[2:3], v[214:215]
	v_add_f32_e32 v216, v200, v201
	v_add_f32_e32 v217, v202, v203
	v_add_f32_e32 v218, v204, v205
	v_add_f32_e32 v219, v206, v207
	v_add_f32_e32 v220, v208, v209
	v_add_f32_e32 v221, v210, v211
	v_add_f32_e32 v222, v212, v213
	v_add_f32_e32 v223, v214, v215
	v_and_b32_e32 v224, 63, v154
	v_xor_b32_e32 v225, 32, v224
	v_xor_b32_e32 v224, 16, v224
	v_lshlrev_b32_e32 v224, 2, v224
	v_lshlrev_b32_e32 v225, 2, v225
	ds_bpermute_b32 v226, v224, v216
	ds_bpermute_b32 v227, v224, v217
	ds_bpermute_b32 v228, v224, v218
	ds_bpermute_b32 v229, v224, v219
	ds_bpermute_b32 v230, v224, v220
	ds_bpermute_b32 v231, v224, v221
	ds_bpermute_b32 v232, v224, v222
	ds_bpermute_b32 v233, v224, v223
	s_waitcnt lgkmcnt(0)
	v_add_f32_e32 v216, v216, v226
	v_add_f32_e32 v217, v217, v227
	v_add_f32_e32 v218, v218, v228
	v_add_f32_e32 v219, v219, v229
	v_add_f32_e32 v220, v220, v230
	v_add_f32_e32 v221, v221, v231
	v_add_f32_e32 v222, v222, v232
	v_add_f32_e32 v223, v223, v233
	ds_bpermute_b32 v226, v225, v216
	ds_bpermute_b32 v227, v225, v217
	ds_bpermute_b32 v228, v225, v218
	ds_bpermute_b32 v229, v225, v219
	ds_bpermute_b32 v230, v225, v220
	ds_bpermute_b32 v231, v225, v221
	ds_bpermute_b32 v232, v225, v222
	ds_bpermute_b32 v233, v225, v223
	s_waitcnt lgkmcnt(0)
	v_add_f32_e32 v216, v216, v226
	v_add_f32_e32 v217, v217, v227
	v_add_f32_e32 v218, v218, v228
	v_add_f32_e32 v219, v219, v229
	v_add_f32_e32 v220, v220, v230
	v_add_f32_e32 v221, v221, v231
	v_add_f32_e32 v222, v222, v232
	v_add_f32_e32 v223, v223, v233
	v_bfe_u32 v234, v154, 6, 2
	v_lshlrev_b32_e32 v234, 8, v234
	v_lshrrev_b32_e32 v235, 8, v154
	v_lshl_add_u32 v234, v235, 6, v234
	v_and_b32_e32 v235, 15, v154
	v_add_u32_e32 v234, v234, v235
	v_lshlrev_b32_e32 v234, 2, v234
	ds_write_b32 v234, v216 offset:0
	ds_write_b32 v234, v217 offset:64
	ds_write_b32 v234, v218 offset:128
	ds_write_b32 v234, v219 offset:192
	ds_write_b32 v234, v220 offset:512
	ds_write_b32 v234, v221 offset:576
	ds_write_b32 v234, v222 offset:640
	ds_write_b32 v234, v223 offset:704
	s_waitcnt lgkmcnt(0)
	s_barrier
	v_cmp_gt_u32_e32 vcc, 0x100, v154
	s_and_saveexec_b64 s[48:49], vcc
	v_lshlrev_b32_e32 v235, 2, v154
	ds_read_b32 v236, v235
	ds_read_b32 v237, v235 offset:1024
	ds_read_b32 v238, v235 offset:2048
	ds_read_b32 v239, v235 offset:3072
	s_lshl_b32 s50, s4, 3
	s_and_b32 s50, s50, 56
	s_bfe_u32 s51, s4, 0x30003
	s_or_b32 s50, s50, s51
	s_lshl_b32 s50, s50, 2
	s_lshr_b32 s51, s4, 6
	s_or_b32 s50, s50, s51
	s_lshl_b32 s50, s50, 10
	s_add_u32 s50, s50, s72
	s_addc_u32 s51, s73, 0
	s_add_u32 s50, s50, 0x19500000
	s_addc_u32 s51, s51, 0
	s_waitcnt lgkmcnt(0)
	v_add_f32_e32 v236, v236, v237
	v_add_f32_e32 v238, v238, v239
	v_add_f32_e32 v236, v236, v238
	global_store_dword v235, v236, s[50:51]
	s_mov_b64 exec, s[48:49]
	s_mov_b32 s92, s4
	v_mov_b64_e32 v[242:243], v[0:1]
	v_mov_b64_e32 v[244:245], v[2:3]
	v_mov_b64_e32 v[246:247], v[4:5]
	v_mov_b64_e32 v[248:249], v[6:7]
	s_add_i32 s4, s4, s74
	s_add_i32 s9, s9, s20
	s_cmpk_lt_i32 s4, 0x100
	s_cbranch_scc0 .LBB0_705
